# same as the previous best but the SiLU gate quotient is computed as reciprocal + one Newton step + residual correction + v_div_fixup (IEEE quotient without the range scaling, denominators are >= 1) in
# baseline (speedup 1.0000x reference)
.LBB0_216:
	s_andn2_b64 vcc, exec, s[84:85]
	s_cbranch_vccnz .LBB0_218
	v_mov_b32_e32 v0, v151
	s_mov_b32 s4, 0xfffffc0
	v_and_b32_e32 v66, 64, v0
	v_and_b32_e32 v67, 15, v0
	v_lshrrev_b32_e32 v0, 1, v0
	v_and_or_b32 v67, v0, s4, v67
	v_and_b32_e32 v0, 24, v0
	v_lshl_or_b32 v0, v66, 1, v0
	s_movk_i32 s4, 0x110
	v_mad_u64_u32 v[66:67], s[4:5], v67, s4, v[0:1]
	v_mul_f32_e32 v0, 0xbfb8aa3b, v62
	v_exp_f32_e32 v68, v0
	v_mul_f32_e32 v0, 0xbfb8aa3b, v63
	v_exp_f32_e32 v69, v0
	s_nop 0
	v_pk_add_f32 v[68:69], v[68:69], 1.0 op_sel_hi:[1,0]
	s_nop 0
	v_rcp_f32_e32 v67, v69
	s_nop 0
	v_fma_f32 v70, -v69, v67, 1.0
	v_fmac_f32_e32 v67, v70, v67
	v_mul_f32_e32 v71, v63, v67
	v_fma_f32 v72, -v69, v71, v63
	v_fmac_f32_e32 v71, v72, v67
	v_div_fixup_f32 v0, v71, v69, v63
	v_rcp_f32_e32 v67, v68
	s_nop 0
	v_fma_f32 v69, -v68, v67, 1.0
	v_fmac_f32_e32 v67, v69, v67
	v_mul_f32_e32 v70, v62, v67
	v_fma_f32 v71, -v68, v70, v62
	v_fmac_f32_e32 v70, v71, v67
	v_div_fixup_f32 v62, v70, v68, v62
	v_cvt_pk_bf16_f32 v62, v62, v0
	v_mul_f32_e32 v0, 0xbfb8aa3b, v64
	v_exp_f32_e32 v68, v0
	v_mul_f32_e32 v0, 0xbfb8aa3b, v65
	v_exp_f32_e32 v69, v0
	s_nop 0
	v_pk_add_f32 v[68:69], v[68:69], 1.0 op_sel_hi:[1,0]
	s_nop 0
	v_rcp_f32_e32 v63, v69
	s_nop 0
	v_fma_f32 v67, -v69, v63, 1.0
	v_fmac_f32_e32 v63, v67, v63
	v_mul_f32_e32 v70, v65, v63
	v_fma_f32 v71, -v69, v70, v65
	v_fmac_f32_e32 v70, v71, v63
	v_div_fixup_f32 v0, v70, v69, v65
	v_rcp_f32_e32 v65, v68
	s_nop 0
	v_fma_f32 v67, -v68, v65, 1.0
	v_fmac_f32_e32 v65, v67, v65
	v_mul_f32_e32 v69, v64, v65
	v_fma_f32 v70, -v68, v69, v64
	v_fmac_f32_e32 v69, v70, v65
	v_div_fixup_f32 v63, v69, v68, v64
	v_cvt_pk_bf16_f32 v63, v63, v0
	v_mul_f32_e32 v0, 0xbfb8aa3b, v58
	v_exp_f32_e32 v64, v0
	v_mul_f32_e32 v0, 0xbfb8aa3b, v59
	v_exp_f32_e32 v65, v0
	s_nop 0
	v_pk_add_f32 v[64:65], v[64:65], 1.0 op_sel_hi:[1,0]
	s_nop 0
	v_rcp_f32_e32 v67, v65
	s_nop 0
	v_fma_f32 v68, -v65, v67, 1.0
	v_fmac_f32_e32 v67, v68, v67
	v_mul_f32_e32 v69, v59, v67
	v_fma_f32 v70, -v65, v69, v59
	v_fmac_f32_e32 v69, v70, v67
	v_div_fixup_f32 v0, v69, v65, v59
	v_rcp_f32_e32 v65, v64
	s_nop 0
	v_fma_f32 v67, -v64, v65, 1.0
	v_fmac_f32_e32 v65, v67, v65
	v_mul_f32_e32 v68, v58, v65
	v_fma_f32 v69, -v64, v68, v58
	v_fmac_f32_e32 v68, v69, v65
	v_div_fixup_f32 v58, v68, v64, v58
	v_cvt_pk_bf16_f32 v58, v58, v0
	v_mul_f32_e32 v0, 0xbfb8aa3b, v60
	v_exp_f32_e32 v64, v0
	v_mul_f32_e32 v0, 0xbfb8aa3b, v61
	v_exp_f32_e32 v65, v0
	s_nop 0
	v_pk_add_f32 v[64:65], v[64:65], 1.0 op_sel_hi:[1,0]
	s_nop 0
	v_rcp_f32_e32 v59, v65
	s_nop 0
	v_fma_f32 v67, -v65, v59, 1.0
	v_fmac_f32_e32 v59, v67, v59
	v_mul_f32_e32 v68, v61, v59
	v_fma_f32 v69, -v65, v68, v61
	v_fmac_f32_e32 v68, v69, v59
	v_div_fixup_f32 v0, v68, v65, v61
	v_rcp_f32_e32 v61, v64
	s_nop 0
	v_fma_f32 v65, -v64, v61, 1.0
	v_fmac_f32_e32 v61, v65, v61
	v_mul_f32_e32 v67, v60, v61
	v_fma_f32 v68, -v64, v67, v60
	v_fmac_f32_e32 v67, v68, v61
	v_div_fixup_f32 v59, v67, v64, v60
	v_cvt_pk_bf16_f32 v59, v59, v0
	v_mul_f32_e32 v0, 0xbfb8aa3b, v54
	ds_write2_b64 v66, v[62:63], v[58:59] offset1:4
	v_exp_f32_e32 v58, v0
	v_mul_f32_e32 v0, 0xbfb8aa3b, v55
	v_exp_f32_e32 v59, v0
	s_nop 0
	v_pk_add_f32 v[58:59], v[58:59], 1.0 op_sel_hi:[1,0]
	s_nop 0
	v_rcp_f32_e32 v60, v59
	s_nop 0
	v_fma_f32 v61, -v59, v60, 1.0
	v_fmac_f32_e32 v60, v61, v60
	v_mul_f32_e32 v62, v55, v60
	v_fma_f32 v63, -v59, v62, v55
	v_fmac_f32_e32 v62, v63, v60
	v_div_fixup_f32 v0, v62, v59, v55
	v_rcp_f32_e32 v59, v58
	s_nop 0
	v_fma_f32 v60, -v58, v59, 1.0
	v_fmac_f32_e32 v59, v60, v59
	v_mul_f32_e32 v61, v54, v59
	v_fma_f32 v62, -v58, v61, v54
	v_fmac_f32_e32 v61, v62, v59
	v_div_fixup_f32 v54, v61, v58, v54
	v_cvt_pk_bf16_f32 v54, v54, v0
	v_mul_f32_e32 v0, 0xbfb8aa3b, v56
	v_exp_f32_e32 v58, v0
	v_mul_f32_e32 v0, 0xbfb8aa3b, v57
	v_exp_f32_e32 v59, v0
	s_nop 0
	v_pk_add_f32 v[58:59], v[58:59], 1.0 op_sel_hi:[1,0]
	s_nop 0
	v_rcp_f32_e32 v55, v59
	s_nop 0
	v_fma_f32 v60, -v59, v55, 1.0
	v_fmac_f32_e32 v55, v60, v55
	v_mul_f32_e32 v61, v57, v55
	v_fma_f32 v62, -v59, v61, v57
	v_fmac_f32_e32 v61, v62, v55
	v_div_fixup_f32 v0, v61, v59, v57
	v_rcp_f32_e32 v57, v58
	s_nop 0
	v_fma_f32 v59, -v58, v57, 1.0
	v_fmac_f32_e32 v57, v59, v57
	v_mul_f32_e32 v60, v56, v57
	v_fma_f32 v61, -v58, v60, v56
	v_fmac_f32_e32 v60, v61, v57
	v_div_fixup_f32 v55, v60, v58, v56
	v_cvt_pk_bf16_f32 v55, v55, v0
	v_mul_f32_e32 v0, 0xbfb8aa3b, v50
	v_exp_f32_e32 v56, v0
	v_mul_f32_e32 v0, 0xbfb8aa3b, v51
	v_exp_f32_e32 v57, v0
	s_nop 0
	v_pk_add_f32 v[56:57], v[56:57], 1.0 op_sel_hi:[1,0]
	s_nop 0
	v_rcp_f32_e32 v58, v57
	s_nop 0
	v_fma_f32 v59, -v57, v58, 1.0
	v_fmac_f32_e32 v58, v59, v58
	v_mul_f32_e32 v60, v51, v58
	v_fma_f32 v61, -v57, v60, v51
	v_fmac_f32_e32 v60, v61, v58
	v_div_fixup_f32 v0, v60, v57, v51
	v_rcp_f32_e32 v57, v56
	s_nop 0
	v_fma_f32 v58, -v56, v57, 1.0
	v_fmac_f32_e32 v57, v58, v57
	v_mul_f32_e32 v59, v50, v57
	v_fma_f32 v60, -v56, v59, v50
	v_fmac_f32_e32 v59, v60, v57
	v_div_fixup_f32 v50, v59, v56, v50
	v_cvt_pk_bf16_f32 v50, v50, v0
	v_mul_f32_e32 v0, 0xbfb8aa3b, v52
	v_exp_f32_e32 v56, v0
	v_mul_f32_e32 v0, 0xbfb8aa3b, v53
	v_exp_f32_e32 v57, v0
	s_nop 0
	v_pk_add_f32 v[56:57], v[56:57], 1.0 op_sel_hi:[1,0]
	s_nop 0
	v_rcp_f32_e32 v51, v57
	s_nop 0
	v_fma_f32 v58, -v57, v51, 1.0
	v_fmac_f32_e32 v51, v58, v51
	v_mul_f32_e32 v59, v53, v51
	v_fma_f32 v60, -v57, v59, v53
	v_fmac_f32_e32 v59, v60, v51
	v_div_fixup_f32 v0, v59, v57, v53
	v_rcp_f32_e32 v53, v56
	s_nop 0
	v_fma_f32 v57, -v56, v53, 1.0
	v_fmac_f32_e32 v53, v57, v53
	v_mul_f32_e32 v58, v52, v53
	v_fma_f32 v59, -v56, v58, v52
	v_fmac_f32_e32 v58, v59, v53
	v_div_fixup_f32 v51, v58, v56, v52
	v_cvt_pk_bf16_f32 v51, v51, v0
	v_mul_f32_e32 v0, 0xbfb8aa3b, v46
	ds_write2_b64 v66, v[54:55], v[50:51] offset0:8 offset1:12
	v_exp_f32_e32 v50, v0
	v_mul_f32_e32 v0, 0xbfb8aa3b, v47
	v_exp_f32_e32 v51, v0
	s_nop 0
	v_pk_add_f32 v[50:51], v[50:51], 1.0 op_sel_hi:[1,0]
	s_nop 0
	v_rcp_f32_e32 v52, v51
	s_nop 0
	v_fma_f32 v53, -v51, v52, 1.0
	v_fmac_f32_e32 v52, v53, v52
	v_mul_f32_e32 v54, v47, v52
	v_fma_f32 v55, -v51, v54, v47
	v_fmac_f32_e32 v54, v55, v52
	v_div_fixup_f32 v0, v54, v51, v47
	v_rcp_f32_e32 v51, v50
	s_nop 0
	v_fma_f32 v52, -v50, v51, 1.0
	v_fmac_f32_e32 v51, v52, v51
	v_mul_f32_e32 v53, v46, v51
	v_fma_f32 v54, -v50, v53, v46
	v_fmac_f32_e32 v53, v54, v51
	v_div_fixup_f32 v46, v53, v50, v46
	v_cvt_pk_bf16_f32 v46, v46, v0
	v_mul_f32_e32 v0, 0xbfb8aa3b, v48
	v_exp_f32_e32 v50, v0
	v_mul_f32_e32 v0, 0xbfb8aa3b, v49
	v_exp_f32_e32 v51, v0
	s_nop 0
	v_pk_add_f32 v[50:51], v[50:51], 1.0 op_sel_hi:[1,0]
	s_nop 0
	v_rcp_f32_e32 v47, v51
	s_nop 0
	v_fma_f32 v52, -v51, v47, 1.0
	v_fmac_f32_e32 v47, v52, v47
	v_mul_f32_e32 v53, v49, v47
	v_fma_f32 v54, -v51, v53, v49
	v_fmac_f32_e32 v53, v54, v47
	v_div_fixup_f32 v0, v53, v51, v49
	v_rcp_f32_e32 v49, v50
	s_nop 0
	v_fma_f32 v51, -v50, v49, 1.0
	v_fmac_f32_e32 v49, v51, v49
	v_mul_f32_e32 v52, v48, v49
	v_fma_f32 v53, -v50, v52, v48
	v_fmac_f32_e32 v52, v53, v49
	v_div_fixup_f32 v47, v52, v50, v48
	v_cvt_pk_bf16_f32 v47, v47, v0
	v_mul_f32_e32 v0, 0xbfb8aa3b, v42
	v_exp_f32_e32 v48, v0
	v_mul_f32_e32 v0, 0xbfb8aa3b, v43
	v_exp_f32_e32 v49, v0
	s_nop 0
	v_pk_add_f32 v[48:49], v[48:49], 1.0 op_sel_hi:[1,0]
	s_nop 0
	v_rcp_f32_e32 v50, v49
	s_nop 0
	v_fma_f32 v51, -v49, v50, 1.0
	v_fmac_f32_e32 v50, v51, v50
	v_mul_f32_e32 v52, v43, v50
	v_fma_f32 v53, -v49, v52, v43
	v_fmac_f32_e32 v52, v53, v50
	v_div_fixup_f32 v0, v52, v49, v43
	v_rcp_f32_e32 v49, v48
	s_nop 0
	v_fma_f32 v50, -v48, v49, 1.0
	v_fmac_f32_e32 v49, v50, v49
	v_mul_f32_e32 v51, v42, v49
	v_fma_f32 v52, -v48, v51, v42
	v_fmac_f32_e32 v51, v52, v49
	v_div_fixup_f32 v42, v51, v48, v42
	v_cvt_pk_bf16_f32 v42, v42, v0
	v_mul_f32_e32 v0, 0xbfb8aa3b, v44
	v_exp_f32_e32 v48, v0
	v_mul_f32_e32 v0, 0xbfb8aa3b, v45
	v_exp_f32_e32 v49, v0
	s_nop 0
	v_pk_add_f32 v[48:49], v[48:49], 1.0 op_sel_hi:[1,0]
	s_nop 0
	v_rcp_f32_e32 v43, v49
	s_nop 0
	v_fma_f32 v50, -v49, v43, 1.0
	v_fmac_f32_e32 v43, v50, v43
	v_mul_f32_e32 v51, v45, v43
	v_fma_f32 v52, -v49, v51, v45
	v_fmac_f32_e32 v51, v52, v43
	v_div_fixup_f32 v0, v51, v49, v45
	v_rcp_f32_e32 v45, v48
	s_nop 0
	v_fma_f32 v49, -v48, v45, 1.0
	v_fmac_f32_e32 v45, v49, v45
	v_mul_f32_e32 v50, v44, v45
	v_fma_f32 v51, -v48, v50, v44
	v_fmac_f32_e32 v50, v51, v45
	v_div_fixup_f32 v43, v50, v48, v44
	v_cvt_pk_bf16_f32 v43, v43, v0
	v_add_u32_e32 v0, 0x1000, v66
	ds_write2_b64 v0, v[46:47], v[42:43] offset0:32 offset1:36
	v_mul_f32_e32 v42, 0xbfb8aa3b, v38
	v_mul_f32_e32 v43, 0xbfb8aa3b, v39
	v_exp_f32_e32 v42, v42
	v_exp_f32_e32 v43, v43
	s_nop 0
	v_pk_add_f32 v[42:43], v[42:43], 1.0 op_sel_hi:[1,0]
	s_nop 0
	v_rcp_f32_e32 v45, v43
	s_nop 0
	v_fma_f32 v46, -v43, v45, 1.0
	v_fmac_f32_e32 v45, v46, v45
	v_mul_f32_e32 v47, v39, v45
	v_fma_f32 v48, -v43, v47, v39
	v_fmac_f32_e32 v47, v48, v45
	v_div_fixup_f32 v39, v47, v43, v39
	v_rcp_f32_e32 v44, v42
	s_nop 0
	v_fma_f32 v45, -v42, v44, 1.0
	v_fmac_f32_e32 v44, v45, v44
	v_mul_f32_e32 v46, v38, v44
	v_fma_f32 v47, -v42, v46, v38
	v_fmac_f32_e32 v46, v47, v44
	v_div_fixup_f32 v38, v46, v42, v38
	v_cvt_pk_bf16_f32 v38, v38, v39
	v_mul_f32_e32 v39, 0xbfb8aa3b, v40
	v_exp_f32_e32 v42, v39
	v_mul_f32_e32 v39, 0xbfb8aa3b, v41
	v_exp_f32_e32 v43, v39
	s_nop 0
	v_pk_add_f32 v[42:43], v[42:43], 1.0 op_sel_hi:[1,0]
	s_nop 0
	v_rcp_f32_e32 v44, v43
	s_nop 0
	v_fma_f32 v45, -v43, v44, 1.0
	v_fmac_f32_e32 v44, v45, v44
	v_mul_f32_e32 v46, v41, v44
	v_fma_f32 v47, -v43, v46, v41
	v_fmac_f32_e32 v46, v47, v44
	v_div_fixup_f32 v39, v46, v43, v41
	v_rcp_f32_e32 v43, v42
	s_nop 0
	v_fma_f32 v44, -v42, v43, 1.0
	v_fmac_f32_e32 v43, v44, v43
	v_mul_f32_e32 v45, v40, v43
	v_fma_f32 v46, -v42, v45, v40
	v_fmac_f32_e32 v45, v46, v43
	v_div_fixup_f32 v40, v45, v42, v40
	v_cvt_pk_bf16_f32 v39, v40, v39
	v_mul_f32_e32 v40, 0xbfb8aa3b, v34
	v_mul_f32_e32 v41, 0xbfb8aa3b, v35
	v_exp_f32_e32 v40, v40
	v_exp_f32_e32 v41, v41
	s_nop 0
	v_pk_add_f32 v[40:41], v[40:41], 1.0 op_sel_hi:[1,0]
	s_nop 0
	v_rcp_f32_e32 v43, v41
	s_nop 0
	v_fma_f32 v44, -v41, v43, 1.0
	v_fmac_f32_e32 v43, v44, v43
	v_mul_f32_e32 v45, v35, v43
	v_fma_f32 v46, -v41, v45, v35
	v_fmac_f32_e32 v45, v46, v43
	v_div_fixup_f32 v35, v45, v41, v35
	v_rcp_f32_e32 v42, v40
	s_nop 0
	v_fma_f32 v43, -v40, v42, 1.0
	v_fmac_f32_e32 v42, v43, v42
	v_mul_f32_e32 v44, v34, v42
	v_fma_f32 v45, -v40, v44, v34
	v_fmac_f32_e32 v44, v45, v42
	v_div_fixup_f32 v34, v44, v40, v34
	v_cvt_pk_bf16_f32 v34, v34, v35
	v_mul_f32_e32 v35, 0xbfb8aa3b, v36
	v_exp_f32_e32 v40, v35
	v_mul_f32_e32 v35, 0xbfb8aa3b, v37
	v_exp_f32_e32 v41, v35
	s_nop 0
	v_pk_add_f32 v[40:41], v[40:41], 1.0 op_sel_hi:[1,0]
	s_nop 0
	v_rcp_f32_e32 v42, v41
	s_nop 0
	v_fma_f32 v43, -v41, v42, 1.0
	v_fmac_f32_e32 v42, v43, v42
	v_mul_f32_e32 v44, v37, v42
	v_fma_f32 v45, -v41, v44, v37
	v_fmac_f32_e32 v44, v45, v42
	v_div_fixup_f32 v35, v44, v41, v37
	v_rcp_f32_e32 v41, v40
	s_nop 0
	v_fma_f32 v42, -v40, v41, 1.0
	v_fmac_f32_e32 v41, v42, v41
	v_mul_f32_e32 v43, v36, v41
	v_fma_f32 v44, -v40, v43, v36
	v_fmac_f32_e32 v43, v44, v41
	v_div_fixup_f32 v36, v43, v40, v36
	v_cvt_pk_bf16_f32 v35, v36, v35
	ds_write2_b64 v0, v[38:39], v[34:35] offset0:40 offset1:44
	v_mul_f32_e32 v0, 0xbfb8aa3b, v30
	v_exp_f32_e32 v34, v0
	v_mul_f32_e32 v0, 0xbfb8aa3b, v31
	v_exp_f32_e32 v35, v0
	s_nop 0
	v_pk_add_f32 v[34:35], v[34:35], 1.0 op_sel_hi:[1,0]
	s_nop 0
	v_rcp_f32_e32 v36, v35
	s_nop 0
	v_fma_f32 v37, -v35, v36, 1.0
	v_fmac_f32_e32 v36, v37, v36
	v_mul_f32_e32 v38, v31, v36
	v_fma_f32 v39, -v35, v38, v31
	v_fmac_f32_e32 v38, v39, v36
	v_div_fixup_f32 v0, v38, v35, v31
	v_rcp_f32_e32 v35, v34
	s_nop 0
	v_fma_f32 v36, -v34, v35, 1.0
	v_fmac_f32_e32 v35, v36, v35
	v_mul_f32_e32 v37, v30, v35
	v_fma_f32 v38, -v34, v37, v30
	v_fmac_f32_e32 v37, v38, v35
	v_div_fixup_f32 v30, v37, v34, v30
	v_cvt_pk_bf16_f32 v30, v30, v0
	v_mul_f32_e32 v0, 0xbfb8aa3b, v32
	v_exp_f32_e32 v34, v0
	v_mul_f32_e32 v0, 0xbfb8aa3b, v33
	v_exp_f32_e32 v35, v0
	s_nop 0
	v_pk_add_f32 v[34:35], v[34:35], 1.0 op_sel_hi:[1,0]
	s_nop 0
	v_rcp_f32_e32 v31, v35
	s_nop 0
	v_fma_f32 v36, -v35, v31, 1.0
	v_fmac_f32_e32 v31, v36, v31
	v_mul_f32_e32 v37, v33, v31
	v_fma_f32 v38, -v35, v37, v33
	v_fmac_f32_e32 v37, v38, v31
	v_div_fixup_f32 v0, v37, v35, v33
	v_rcp_f32_e32 v33, v34
	s_nop 0
	v_fma_f32 v35, -v34, v33, 1.0
	v_fmac_f32_e32 v33, v35, v33
	v_mul_f32_e32 v36, v32, v33
	v_fma_f32 v37, -v34, v36, v32
	v_fmac_f32_e32 v36, v37, v33
	v_div_fixup_f32 v31, v36, v34, v32
	v_cvt_pk_bf16_f32 v31, v31, v0
	v_mul_f32_e32 v0, 0xbfb8aa3b, v26
	v_exp_f32_e32 v32, v0
	v_mul_f32_e32 v0, 0xbfb8aa3b, v27
	v_exp_f32_e32 v33, v0
	s_nop 0
	v_pk_add_f32 v[32:33], v[32:33], 1.0 op_sel_hi:[1,0]
	s_nop 0
	v_rcp_f32_e32 v34, v33
	s_nop 0
	v_fma_f32 v35, -v33, v34, 1.0
	v_fmac_f32_e32 v34, v35, v34
	v_mul_f32_e32 v36, v27, v34
	v_fma_f32 v37, -v33, v36, v27
	v_fmac_f32_e32 v36, v37, v34
	v_div_fixup_f32 v0, v36, v33, v27
	v_rcp_f32_e32 v33, v32
	s_nop 0
	v_fma_f32 v34, -v32, v33, 1.0
	v_fmac_f32_e32 v33, v34, v33
	v_mul_f32_e32 v35, v26, v33
	v_fma_f32 v36, -v32, v35, v26
	v_fmac_f32_e32 v35, v36, v33
	v_div_fixup_f32 v26, v35, v32, v26
	v_cvt_pk_bf16_f32 v26, v26, v0
	v_mul_f32_e32 v0, 0xbfb8aa3b, v28
	v_exp_f32_e32 v32, v0
	v_mul_f32_e32 v0, 0xbfb8aa3b, v29
	v_exp_f32_e32 v33, v0
	s_nop 0
	v_pk_add_f32 v[32:33], v[32:33], 1.0 op_sel_hi:[1,0]
	s_nop 0
	v_rcp_f32_e32 v27, v33
	s_nop 0
	v_fma_f32 v34, -v33, v27, 1.0
	v_fmac_f32_e32 v27, v34, v27
	v_mul_f32_e32 v35, v29, v27
	v_fma_f32 v36, -v33, v35, v29
	v_fmac_f32_e32 v35, v36, v27
	v_div_fixup_f32 v0, v35, v33, v29
	v_rcp_f32_e32 v29, v32
	s_nop 0
	v_fma_f32 v33, -v32, v29, 1.0
	v_fmac_f32_e32 v29, v33, v29
	v_mul_f32_e32 v34, v28, v29
	v_fma_f32 v35, -v32, v34, v28
	v_fmac_f32_e32 v34, v35, v29
	v_div_fixup_f32 v27, v34, v32, v28
	v_cvt_pk_bf16_f32 v27, v27, v0
	v_add_u32_e32 v0, 0x2000, v66
	ds_write2_b64 v0, v[30:31], v[26:27] offset0:64 offset1:68
	v_mul_f32_e32 v26, 0xbfb8aa3b, v22
	v_mul_f32_e32 v27, 0xbfb8aa3b, v23
	v_exp_f32_e32 v26, v26
	v_exp_f32_e32 v27, v27
	s_nop 0
	v_pk_add_f32 v[26:27], v[26:27], 1.0 op_sel_hi:[1,0]
	s_nop 0
	v_rcp_f32_e32 v29, v27
	s_nop 0
	v_fma_f32 v30, -v27, v29, 1.0
	v_fmac_f32_e32 v29, v30, v29
	v_mul_f32_e32 v31, v23, v29
	v_fma_f32 v32, -v27, v31, v23
	v_fmac_f32_e32 v31, v32, v29
	v_div_fixup_f32 v23, v31, v27, v23
	v_rcp_f32_e32 v28, v26
	s_nop 0
	v_fma_f32 v29, -v26, v28, 1.0
	v_fmac_f32_e32 v28, v29, v28
	v_mul_f32_e32 v30, v22, v28
	v_fma_f32 v31, -v26, v30, v22
	v_fmac_f32_e32 v30, v31, v28
	v_div_fixup_f32 v22, v30, v26, v22
	v_cvt_pk_bf16_f32 v22, v22, v23
	v_mul_f32_e32 v23, 0xbfb8aa3b, v24
	v_exp_f32_e32 v26, v23
	v_mul_f32_e32 v23, 0xbfb8aa3b, v25
	v_exp_f32_e32 v27, v23
	s_nop 0
	v_pk_add_f32 v[26:27], v[26:27], 1.0 op_sel_hi:[1,0]
	s_nop 0
	v_rcp_f32_e32 v28, v27
	s_nop 0
	v_fma_f32 v29, -v27, v28, 1.0
	v_fmac_f32_e32 v28, v29, v28
	v_mul_f32_e32 v30, v25, v28
	v_fma_f32 v31, -v27, v30, v25
	v_fmac_f32_e32 v30, v31, v28
	v_div_fixup_f32 v23, v30, v27, v25
	v_rcp_f32_e32 v27, v26
	s_nop 0
	v_fma_f32 v28, -v26, v27, 1.0
	v_fmac_f32_e32 v27, v28, v27
	v_mul_f32_e32 v29, v24, v27
	v_fma_f32 v30, -v26, v29, v24
	v_fmac_f32_e32 v29, v30, v27
	v_div_fixup_f32 v24, v29, v26, v24
	v_cvt_pk_bf16_f32 v23, v24, v23
	v_mul_f32_e32 v24, 0xbfb8aa3b, v18
	v_mul_f32_e32 v25, 0xbfb8aa3b, v19
	v_exp_f32_e32 v24, v24
	v_exp_f32_e32 v25, v25
	s_nop 0
	v_pk_add_f32 v[24:25], v[24:25], 1.0 op_sel_hi:[1,0]
	s_nop 0
	v_rcp_f32_e32 v27, v25
	s_nop 0
	v_fma_f32 v28, -v25, v27, 1.0
	v_fmac_f32_e32 v27, v28, v27
	v_mul_f32_e32 v29, v19, v27
	v_fma_f32 v30, -v25, v29, v19
	v_fmac_f32_e32 v29, v30, v27
	v_div_fixup_f32 v19, v29, v25, v19
	v_rcp_f32_e32 v26, v24
	s_nop 0
	v_fma_f32 v27, -v24, v26, 1.0
	v_fmac_f32_e32 v26, v27, v26
	v_mul_f32_e32 v28, v18, v26
	v_fma_f32 v29, -v24, v28, v18
	v_fmac_f32_e32 v28, v29, v26
	v_div_fixup_f32 v18, v28, v24, v18
	v_cvt_pk_bf16_f32 v18, v18, v19
	v_mul_f32_e32 v19, 0xbfb8aa3b, v20
	v_exp_f32_e32 v24, v19
	v_mul_f32_e32 v19, 0xbfb8aa3b, v21
	v_exp_f32_e32 v25, v19
	s_nop 0
	v_pk_add_f32 v[24:25], v[24:25], 1.0 op_sel_hi:[1,0]
	s_nop 0
	v_rcp_f32_e32 v26, v25
	s_nop 0
	v_fma_f32 v27, -v25, v26, 1.0
	v_fmac_f32_e32 v26, v27, v26
	v_mul_f32_e32 v28, v21, v26
	v_fma_f32 v29, -v25, v28, v21
	v_fmac_f32_e32 v28, v29, v26
	v_div_fixup_f32 v19, v28, v25, v21
	v_rcp_f32_e32 v25, v24
	s_nop 0
	v_fma_f32 v26, -v24, v25, 1.0
	v_fmac_f32_e32 v25, v26, v25
	v_mul_f32_e32 v27, v20, v25
	v_fma_f32 v28, -v24, v27, v20
	v_fmac_f32_e32 v27, v28, v25
	v_div_fixup_f32 v20, v27, v24, v20
	v_cvt_pk_bf16_f32 v19, v20, v19
	ds_write2_b64 v0, v[22:23], v[18:19] offset0:72 offset1:76
	v_mul_f32_e32 v0, 0xbfb8aa3b, v14
	v_exp_f32_e32 v18, v0
	v_mul_f32_e32 v0, 0xbfb8aa3b, v15
	v_exp_f32_e32 v19, v0
	s_nop 0
	v_pk_add_f32 v[18:19], v[18:19], 1.0 op_sel_hi:[1,0]
	s_nop 0
	v_rcp_f32_e32 v20, v19
	s_nop 0
	v_fma_f32 v21, -v19, v20, 1.0
	v_fmac_f32_e32 v20, v21, v20
	v_mul_f32_e32 v22, v15, v20
	v_fma_f32 v23, -v19, v22, v15
	v_fmac_f32_e32 v22, v23, v20
	v_div_fixup_f32 v0, v22, v19, v15
	v_rcp_f32_e32 v19, v18
	s_nop 0
	v_fma_f32 v20, -v18, v19, 1.0
	v_fmac_f32_e32 v19, v20, v19
	v_mul_f32_e32 v21, v14, v19
	v_fma_f32 v22, -v18, v21, v14
	v_fmac_f32_e32 v21, v22, v19
	v_div_fixup_f32 v14, v21, v18, v14
	v_cvt_pk_bf16_f32 v14, v14, v0
	v_mul_f32_e32 v0, 0xbfb8aa3b, v16
	v_exp_f32_e32 v18, v0
	v_mul_f32_e32 v0, 0xbfb8aa3b, v17
	v_exp_f32_e32 v19, v0
	s_nop 0
	v_pk_add_f32 v[18:19], v[18:19], 1.0 op_sel_hi:[1,0]
	s_nop 0
	v_rcp_f32_e32 v15, v19
	s_nop 0
	v_fma_f32 v20, -v19, v15, 1.0
	v_fmac_f32_e32 v15, v20, v15
	v_mul_f32_e32 v21, v17, v15
	v_fma_f32 v22, -v19, v21, v17
	v_fmac_f32_e32 v21, v22, v15
	v_div_fixup_f32 v0, v21, v19, v17
	v_rcp_f32_e32 v17, v18
	s_nop 0
	v_fma_f32 v19, -v18, v17, 1.0
	v_fmac_f32_e32 v17, v19, v17
	v_mul_f32_e32 v20, v16, v17
	v_fma_f32 v21, -v18, v20, v16
	v_fmac_f32_e32 v20, v21, v17
	v_div_fixup_f32 v15, v20, v18, v16
	v_cvt_pk_bf16_f32 v15, v15, v0
	v_mul_f32_e32 v0, 0xbfb8aa3b, v10
	v_exp_f32_e32 v16, v0
	v_mul_f32_e32 v0, 0xbfb8aa3b, v11
	v_exp_f32_e32 v17, v0
	s_nop 0
	v_pk_add_f32 v[16:17], v[16:17], 1.0 op_sel_hi:[1,0]
	s_nop 0
	v_rcp_f32_e32 v18, v17
	s_nop 0
	v_fma_f32 v19, -v17, v18, 1.0
	v_fmac_f32_e32 v18, v19, v18
	v_mul_f32_e32 v20, v11, v18
	v_fma_f32 v21, -v17, v20, v11
	v_fmac_f32_e32 v20, v21, v18
	v_div_fixup_f32 v0, v20, v17, v11
	v_rcp_f32_e32 v17, v16
	s_nop 0
	v_fma_f32 v18, -v16, v17, 1.0
	v_fmac_f32_e32 v17, v18, v17
	v_mul_f32_e32 v19, v10, v17
	v_fma_f32 v20, -v16, v19, v10
	v_fmac_f32_e32 v19, v20, v17
	v_div_fixup_f32 v10, v19, v16, v10
	v_cvt_pk_bf16_f32 v10, v10, v0
	v_mul_f32_e32 v0, 0xbfb8aa3b, v12
	v_exp_f32_e32 v16, v0
	v_mul_f32_e32 v0, 0xbfb8aa3b, v13
	v_exp_f32_e32 v17, v0
	s_nop 0
	v_pk_add_f32 v[16:17], v[16:17], 1.0 op_sel_hi:[1,0]
	s_nop 0
	v_rcp_f32_e32 v11, v17
	s_nop 0
	v_fma_f32 v18, -v17, v11, 1.0
	v_fmac_f32_e32 v11, v18, v11
	v_mul_f32_e32 v19, v13, v11
	v_fma_f32 v20, -v17, v19, v13
	v_fmac_f32_e32 v19, v20, v11
	v_div_fixup_f32 v0, v19, v17, v13
	v_rcp_f32_e32 v13, v16
	s_nop 0
	v_fma_f32 v17, -v16, v13, 1.0
	v_fmac_f32_e32 v13, v17, v13
	v_mul_f32_e32 v18, v12, v13
	v_fma_f32 v19, -v16, v18, v12
	v_fmac_f32_e32 v18, v19, v13
	v_div_fixup_f32 v11, v18, v16, v12
	v_cvt_pk_bf16_f32 v11, v11, v0
	v_add_u32_e32 v0, 0x3000, v66
	ds_write2_b64 v0, v[14:15], v[10:11] offset0:96 offset1:100
	v_mul_f32_e32 v10, 0xbfb8aa3b, v6
	v_mul_f32_e32 v11, 0xbfb8aa3b, v7
	v_exp_f32_e32 v10, v10
	v_exp_f32_e32 v11, v11
	s_nop 0
	v_pk_add_f32 v[10:11], v[10:11], 1.0 op_sel_hi:[1,0]
	s_nop 0
	v_rcp_f32_e32 v13, v11
	s_nop 0
	v_fma_f32 v14, -v11, v13, 1.0
	v_fmac_f32_e32 v13, v14, v13
	v_mul_f32_e32 v15, v7, v13
	v_fma_f32 v16, -v11, v15, v7
	v_fmac_f32_e32 v15, v16, v13
	v_div_fixup_f32 v7, v15, v11, v7
	v_rcp_f32_e32 v12, v10
	s_nop 0
	v_fma_f32 v13, -v10, v12, 1.0
	v_fmac_f32_e32 v12, v13, v12
	v_mul_f32_e32 v14, v6, v12
	v_fma_f32 v15, -v10, v14, v6
	v_fmac_f32_e32 v14, v15, v12
	v_div_fixup_f32 v6, v14, v10, v6
	v_cvt_pk_bf16_f32 v6, v6, v7
	v_mul_f32_e32 v7, 0xbfb8aa3b, v8
	v_exp_f32_e32 v10, v7
	v_mul_f32_e32 v7, 0xbfb8aa3b, v9
	v_exp_f32_e32 v11, v7
	s_nop 0
	v_pk_add_f32 v[10:11], v[10:11], 1.0 op_sel_hi:[1,0]
	s_nop 0
	v_rcp_f32_e32 v12, v11
	s_nop 0
	v_fma_f32 v13, -v11, v12, 1.0
	v_fmac_f32_e32 v12, v13, v12
	v_mul_f32_e32 v14, v9, v12
	v_fma_f32 v15, -v11, v14, v9
	v_fmac_f32_e32 v14, v15, v12
	v_div_fixup_f32 v7, v14, v11, v9
	v_rcp_f32_e32 v11, v10
	s_nop 0
	v_fma_f32 v12, -v10, v11, 1.0
	v_fmac_f32_e32 v11, v12, v11
	v_mul_f32_e32 v13, v8, v11
	v_fma_f32 v14, -v10, v13, v8
	v_fmac_f32_e32 v13, v14, v11
	v_div_fixup_f32 v8, v13, v10, v8
	v_cvt_pk_bf16_f32 v7, v8, v7
	v_mul_f32_e32 v8, 0xbfb8aa3b, v2
	v_mul_f32_e32 v9, 0xbfb8aa3b, v3
	v_exp_f32_e32 v8, v8
	v_exp_f32_e32 v9, v9
	s_nop 0
	v_pk_add_f32 v[8:9], v[8:9], 1.0 op_sel_hi:[1,0]
	s_nop 0
	v_rcp_f32_e32 v11, v9
	s_nop 0
	v_fma_f32 v12, -v9, v11, 1.0
	v_fmac_f32_e32 v11, v12, v11
	v_mul_f32_e32 v13, v3, v11
	v_fma_f32 v14, -v9, v13, v3
	v_fmac_f32_e32 v13, v14, v11
	v_div_fixup_f32 v3, v13, v9, v3
	v_rcp_f32_e32 v10, v8
	s_nop 0
	v_fma_f32 v11, -v8, v10, 1.0
	v_fmac_f32_e32 v10, v11, v10
	v_mul_f32_e32 v12, v2, v10
	v_fma_f32 v13, -v8, v12, v2
	v_fmac_f32_e32 v12, v13, v10
	v_div_fixup_f32 v2, v12, v8, v2
	v_cvt_pk_bf16_f32 v2, v2, v3
	v_mul_f32_e32 v3, 0xbfb8aa3b, v4
	v_exp_f32_e32 v8, v3
	v_mul_f32_e32 v3, 0xbfb8aa3b, v5
	v_exp_f32_e32 v9, v3
	s_nop 0
	v_pk_add_f32 v[8:9], v[8:9], 1.0 op_sel_hi:[1,0]
	s_nop 0
	v_rcp_f32_e32 v10, v9
	s_nop 0
	v_fma_f32 v11, -v9, v10, 1.0
	v_fmac_f32_e32 v10, v11, v10
	v_mul_f32_e32 v12, v5, v10
	v_fma_f32 v13, -v9, v12, v5
	v_fmac_f32_e32 v12, v13, v10
	v_div_fixup_f32 v3, v12, v9, v5
	v_rcp_f32_e32 v9, v8
	s_nop 0
	v_fma_f32 v10, -v8, v9, 1.0
	v_fmac_f32_e32 v9, v10, v9
	v_mul_f32_e32 v11, v4, v9
	v_fma_f32 v12, -v8, v11, v4
	v_fmac_f32_e32 v11, v12, v9
	v_div_fixup_f32 v4, v11, v8, v4
	v_cvt_pk_bf16_f32 v3, v4, v3
	ds_write2_b64 v0, v[6:7], v[2:3] offset0:104 offset1:108
	s_waitcnt lgkmcnt(0)
	s_barrier

.LBB0_271:
	v_mov_b32_e32 v0, v151
	s_movk_i32 s4, 0xff80
	v_lshrrev_b32_e32 v66, 1, v0
	v_and_b32_e32 v66, 24, v66
	v_and_b32_e32 v68, 0x4f, v0
	v_and_or_b32 v0, v0, s4, v66
	v_mul_f32_e32 v66, 0xbfb8aa3b, v62
	v_mul_f32_e32 v67, 0xbfb8aa3b, v63
	v_exp_f32_e32 v66, v66
	v_exp_f32_e32 v67, v67
	s_nop 0
	v_pk_add_f32 v[66:67], v[66:67], 1.0 op_sel_hi:[1,0]
	s_nop 0
	v_rcp_f32_e32 v70, v67
	s_nop 0
	v_fma_f32 v71, -v67, v70, 1.0
	v_fmac_f32_e32 v70, v71, v70
	v_mul_f32_e32 v72, v63, v70
	v_fma_f32 v73, -v67, v72, v63
	v_fmac_f32_e32 v72, v73, v70
	v_div_fixup_f32 v63, v72, v67, v63
	v_rcp_f32_e32 v69, v66
	s_nop 0
	v_fma_f32 v70, -v66, v69, 1.0
	v_fmac_f32_e32 v69, v70, v69
	v_mul_f32_e32 v71, v62, v69
	v_fma_f32 v72, -v66, v71, v62
	v_fmac_f32_e32 v71, v72, v69
	v_div_fixup_f32 v62, v71, v66, v62
	v_cvt_pk_bf16_f32 v62, v62, v63
	v_mul_f32_e32 v63, 0xbfb8aa3b, v64
	v_exp_f32_e32 v66, v63
	v_mul_f32_e32 v63, 0xbfb8aa3b, v65
	v_exp_f32_e32 v67, v63
	s_nop 0
	v_pk_add_f32 v[66:67], v[66:67], 1.0 op_sel_hi:[1,0]
	s_nop 0
	v_rcp_f32_e32 v69, v67
	s_nop 0
	v_fma_f32 v70, -v67, v69, 1.0
	v_fmac_f32_e32 v69, v70, v69
	v_mul_f32_e32 v71, v65, v69
	v_fma_f32 v72, -v67, v71, v65
	v_fmac_f32_e32 v71, v72, v69
	v_div_fixup_f32 v63, v71, v67, v65
	v_div_scale_f32 v65, s[4:5], v66, v66, v64
	v_rcp_f32_e32 v67, v65
	s_movk_i32 s4, 0x110
	v_mad_u32_u24 v0, v68, s4, v0
	v_fma_f32 v69, -v65, v67, 1.0
	v_fmac_f32_e32 v67, v69, v67
	v_div_scale_f32 v69, vcc, v64, v66, v64
	v_mul_f32_e32 v70, v69, v67
	v_fma_f32 v71, -v65, v70, v69
	v_fmac_f32_e32 v70, v71, v67
	v_fma_f32 v65, -v65, v70, v69
	v_div_fmas_f32 v65, v65, v67, v70
	v_div_fixup_f32 v64, v65, v66, v64
	v_cvt_pk_bf16_f32 v63, v64, v63
	v_mul_f32_e32 v64, 0xbfb8aa3b, v58
	v_mul_f32_e32 v65, 0xbfb8aa3b, v59
	v_exp_f32_e32 v64, v64
	v_exp_f32_e32 v65, v65
	s_nop 0
	v_pk_add_f32 v[64:65], v[64:65], 1.0 op_sel_hi:[1,0]
	s_nop 0
	v_rcp_f32_e32 v67, v65
	s_nop 0
	v_fma_f32 v68, -v65, v67, 1.0
	v_fmac_f32_e32 v67, v68, v67
	v_mul_f32_e32 v69, v59, v67
	v_fma_f32 v70, -v65, v69, v59
	v_fmac_f32_e32 v69, v70, v67
	v_div_fixup_f32 v59, v69, v65, v59
	v_rcp_f32_e32 v66, v64
	s_nop 0
	v_fma_f32 v67, -v64, v66, 1.0
	v_fmac_f32_e32 v66, v67, v66
	v_mul_f32_e32 v68, v58, v66
	v_fma_f32 v69, -v64, v68, v58
	v_fmac_f32_e32 v68, v69, v66
	v_div_fixup_f32 v58, v68, v64, v58
	v_cvt_pk_bf16_f32 v58, v58, v59
	v_mul_f32_e32 v59, 0xbfb8aa3b, v60
	v_exp_f32_e32 v64, v59
	v_mul_f32_e32 v59, 0xbfb8aa3b, v61
	v_exp_f32_e32 v65, v59
	s_nop 0
	v_pk_add_f32 v[64:65], v[64:65], 1.0 op_sel_hi:[1,0]
	s_nop 0
	v_rcp_f32_e32 v66, v65
	s_nop 0
	v_fma_f32 v67, -v65, v66, 1.0
	v_fmac_f32_e32 v66, v67, v66
	v_mul_f32_e32 v68, v61, v66
	v_fma_f32 v69, -v65, v68, v61
	v_fmac_f32_e32 v68, v69, v66
	v_div_fixup_f32 v59, v68, v65, v61
	v_rcp_f32_e32 v65, v64
	s_nop 0
	v_fma_f32 v66, -v64, v65, 1.0
	v_fmac_f32_e32 v65, v66, v65
	v_mul_f32_e32 v67, v60, v65
	v_fma_f32 v68, -v64, v67, v60
	v_fmac_f32_e32 v67, v68, v65
	v_div_fixup_f32 v60, v67, v64, v60
	v_cvt_pk_bf16_f32 v59, v60, v59
	v_mul_f32_e32 v60, 0xbfb8aa3b, v54
	v_mul_f32_e32 v61, 0xbfb8aa3b, v55
	v_exp_f32_e32 v60, v60
	v_exp_f32_e32 v61, v61
	s_nop 0
	v_pk_add_f32 v[60:61], v[60:61], 1.0 op_sel_hi:[1,0]
	s_nop 0
	v_rcp_f32_e32 v65, v61
	s_nop 0
	v_fma_f32 v66, -v61, v65, 1.0
	v_fmac_f32_e32 v65, v66, v65
	v_mul_f32_e32 v67, v55, v65
	v_fma_f32 v68, -v61, v67, v55
	v_fmac_f32_e32 v67, v68, v65
	v_div_fixup_f32 v55, v67, v61, v55
	v_rcp_f32_e32 v64, v60
	s_nop 0
	v_fma_f32 v65, -v60, v64, 1.0
	v_fmac_f32_e32 v64, v65, v64
	v_mul_f32_e32 v66, v54, v64
	v_fma_f32 v67, -v60, v66, v54
	v_fmac_f32_e32 v66, v67, v64
	v_div_fixup_f32 v54, v66, v60, v54
	v_cvt_pk_bf16_f32 v54, v54, v55
	v_mul_f32_e32 v55, 0xbfb8aa3b, v56
	v_exp_f32_e32 v60, v55
	v_mul_f32_e32 v55, 0xbfb8aa3b, v57
	v_exp_f32_e32 v61, v55
	s_nop 0
	v_pk_add_f32 v[60:61], v[60:61], 1.0 op_sel_hi:[1,0]
	s_nop 0
	v_rcp_f32_e32 v64, v61
	s_nop 0
	v_fma_f32 v65, -v61, v64, 1.0
	v_fmac_f32_e32 v64, v65, v64
	v_mul_f32_e32 v66, v57, v64
	v_fma_f32 v67, -v61, v66, v57
	v_fmac_f32_e32 v66, v67, v64
	v_div_fixup_f32 v55, v66, v61, v57
	v_rcp_f32_e32 v61, v60
	s_nop 0
	v_fma_f32 v64, -v60, v61, 1.0
	v_fmac_f32_e32 v61, v64, v61
	v_mul_f32_e32 v65, v56, v61
	v_fma_f32 v66, -v60, v65, v56
	v_fmac_f32_e32 v65, v66, v61
	v_div_fixup_f32 v56, v65, v60, v56
	v_cvt_pk_bf16_f32 v55, v56, v55
	v_mul_f32_e32 v56, 0xbfb8aa3b, v50
	v_mul_f32_e32 v57, 0xbfb8aa3b, v51
	v_exp_f32_e32 v56, v56
	v_exp_f32_e32 v57, v57
	s_nop 0
	v_pk_add_f32 v[56:57], v[56:57], 1.0 op_sel_hi:[1,0]
	s_nop 0
	v_rcp_f32_e32 v61, v57
	s_nop 0
	v_fma_f32 v64, -v57, v61, 1.0
	v_fmac_f32_e32 v61, v64, v61
	v_mul_f32_e32 v65, v51, v61
	v_fma_f32 v66, -v57, v65, v51
	v_fmac_f32_e32 v65, v66, v61
	v_div_fixup_f32 v51, v65, v57, v51
	v_rcp_f32_e32 v60, v56
	s_nop 0
	v_fma_f32 v61, -v56, v60, 1.0
	v_fmac_f32_e32 v60, v61, v60
	v_mul_f32_e32 v64, v50, v60
	v_fma_f32 v65, -v56, v64, v50
	v_fmac_f32_e32 v64, v65, v60
	v_div_fixup_f32 v50, v64, v56, v50
	v_cvt_pk_bf16_f32 v50, v50, v51
	v_mul_f32_e32 v51, 0xbfb8aa3b, v52
	v_exp_f32_e32 v56, v51
	v_mul_f32_e32 v51, 0xbfb8aa3b, v53
	v_exp_f32_e32 v57, v51
	s_nop 0
	v_pk_add_f32 v[56:57], v[56:57], 1.0 op_sel_hi:[1,0]
	s_nop 0
	v_rcp_f32_e32 v60, v57
	s_nop 0
	v_fma_f32 v61, -v57, v60, 1.0
	v_fmac_f32_e32 v60, v61, v60
	v_mul_f32_e32 v64, v53, v60
	v_fma_f32 v65, -v57, v64, v53
	v_fmac_f32_e32 v64, v65, v60
	v_div_fixup_f32 v51, v64, v57, v53
	v_rcp_f32_e32 v57, v56
	s_nop 0
	v_fma_f32 v60, -v56, v57, 1.0
	v_fmac_f32_e32 v57, v60, v57
	v_mul_f32_e32 v61, v52, v57
	v_fma_f32 v64, -v56, v61, v52
	v_fmac_f32_e32 v61, v64, v57
	v_div_fixup_f32 v52, v61, v56, v52
	v_cvt_pk_bf16_f32 v51, v52, v51
	v_mul_f32_e32 v52, 0xbfb8aa3b, v46
	v_mul_f32_e32 v53, 0xbfb8aa3b, v47
	v_exp_f32_e32 v52, v52
	v_exp_f32_e32 v53, v53
	s_nop 0
	v_pk_add_f32 v[52:53], v[52:53], 1.0 op_sel_hi:[1,0]
	s_nop 0
	v_rcp_f32_e32 v57, v53
	s_nop 0
	v_fma_f32 v60, -v53, v57, 1.0
	v_fmac_f32_e32 v57, v60, v57
	v_mul_f32_e32 v61, v47, v57
	v_fma_f32 v64, -v53, v61, v47
	v_fmac_f32_e32 v61, v64, v57
	v_div_fixup_f32 v47, v61, v53, v47
	v_rcp_f32_e32 v56, v52
	s_nop 0
	v_fma_f32 v57, -v52, v56, 1.0
	v_fmac_f32_e32 v56, v57, v56
	v_mul_f32_e32 v60, v46, v56
	v_fma_f32 v61, -v52, v60, v46
	v_fmac_f32_e32 v60, v61, v56
	v_div_fixup_f32 v46, v60, v52, v46
	v_cvt_pk_bf16_f32 v46, v46, v47
	v_mul_f32_e32 v47, 0xbfb8aa3b, v48
	v_exp_f32_e32 v52, v47
	v_mul_f32_e32 v47, 0xbfb8aa3b, v49
	v_exp_f32_e32 v53, v47
	s_nop 0
	v_pk_add_f32 v[52:53], v[52:53], 1.0 op_sel_hi:[1,0]
	s_nop 0
	v_rcp_f32_e32 v56, v53
	s_nop 0
	v_fma_f32 v57, -v53, v56, 1.0
	v_fmac_f32_e32 v56, v57, v56
	v_mul_f32_e32 v60, v49, v56
	v_fma_f32 v61, -v53, v60, v49
	v_fmac_f32_e32 v60, v61, v56
	v_div_fixup_f32 v47, v60, v53, v49
	v_rcp_f32_e32 v53, v52
	s_nop 0
	v_fma_f32 v56, -v52, v53, 1.0
	v_fmac_f32_e32 v53, v56, v53
	v_mul_f32_e32 v57, v48, v53
	v_fma_f32 v60, -v52, v57, v48
	v_fmac_f32_e32 v57, v60, v53
	v_div_fixup_f32 v48, v57, v52, v48
	v_cvt_pk_bf16_f32 v47, v48, v47
	ds_write2_b64 v0, v[62:63], v[46:47] offset1:4
	v_mul_f32_e32 v46, 0xbfb8aa3b, v42
	v_mul_f32_e32 v47, 0xbfb8aa3b, v43
	v_exp_f32_e32 v46, v46
	v_exp_f32_e32 v47, v47
	s_nop 0
	v_pk_add_f32 v[46:47], v[46:47], 1.0 op_sel_hi:[1,0]
	s_nop 0
	v_rcp_f32_e32 v49, v47
	s_nop 0
	v_fma_f32 v52, -v47, v49, 1.0
	v_fmac_f32_e32 v49, v52, v49
	v_mul_f32_e32 v53, v43, v49
	v_fma_f32 v56, -v47, v53, v43
	v_fmac_f32_e32 v53, v56, v49
	v_div_fixup_f32 v43, v53, v47, v43
	v_rcp_f32_e32 v48, v46
	s_nop 0
	v_fma_f32 v49, -v46, v48, 1.0
	v_fmac_f32_e32 v48, v49, v48
	v_mul_f32_e32 v52, v42, v48
	v_fma_f32 v53, -v46, v52, v42
	v_fmac_f32_e32 v52, v53, v48
	v_div_fixup_f32 v42, v52, v46, v42
	v_cvt_pk_bf16_f32 v46, v42, v43
	v_mul_f32_e32 v42, 0xbfb8aa3b, v44
	v_mul_f32_e32 v43, 0xbfb8aa3b, v45
	v_exp_f32_e32 v42, v42
	v_exp_f32_e32 v43, v43
	s_nop 0
	v_pk_add_f32 v[42:43], v[42:43], 1.0 op_sel_hi:[1,0]
	s_nop 0
	v_rcp_f32_e32 v48, v43
	s_nop 0
	v_fma_f32 v49, -v43, v48, 1.0
	v_fmac_f32_e32 v48, v49, v48
	v_mul_f32_e32 v52, v45, v48
	v_fma_f32 v53, -v43, v52, v45
	v_fmac_f32_e32 v52, v53, v48
	v_div_fixup_f32 v43, v52, v43, v45
	v_rcp_f32_e32 v47, v42
	s_nop 0
	v_fma_f32 v48, -v42, v47, 1.0
	v_fmac_f32_e32 v47, v48, v47
	v_mul_f32_e32 v49, v44, v47
	v_fma_f32 v52, -v42, v49, v44
	v_fmac_f32_e32 v49, v52, v47
	v_div_fixup_f32 v42, v49, v42, v44
	v_cvt_pk_bf16_f32 v47, v42, v43
	v_mul_f32_e32 v43, 0xbfb8aa3b, v38
	v_exp_f32_e32 v44, v43
	v_mul_f32_e32 v43, 0xbfb8aa3b, v39
	v_exp_f32_e32 v45, v43
	v_add_u32_e32 v42, 0x1000, v0
	ds_write2_b64 v42, v[58:59], v[46:47] offset0:32 offset1:36
	v_pk_add_f32 v[44:45], v[44:45], 1.0 op_sel_hi:[1,0]
	s_nop 0
	v_rcp_f32_e32 v46, v45
	s_nop 0
	v_fma_f32 v47, -v45, v46, 1.0
	v_fmac_f32_e32 v46, v47, v46
	v_mul_f32_e32 v48, v39, v46
	v_fma_f32 v49, -v45, v48, v39
	v_fmac_f32_e32 v48, v49, v46
	v_div_fixup_f32 v39, v48, v45, v39
	v_rcp_f32_e32 v45, v44
	s_nop 0
	v_fma_f32 v46, -v44, v45, 1.0
	v_fmac_f32_e32 v45, v46, v45
	v_mul_f32_e32 v47, v38, v45
	v_fma_f32 v48, -v44, v47, v38
	v_fmac_f32_e32 v47, v48, v45
	v_div_fixup_f32 v38, v47, v44, v38
	v_cvt_pk_bf16_f32 v44, v38, v39
	v_mul_f32_e32 v38, 0xbfb8aa3b, v40
	v_mul_f32_e32 v39, 0xbfb8aa3b, v41
	v_exp_f32_e32 v38, v38
	v_exp_f32_e32 v39, v39
	s_nop 0
	v_pk_add_f32 v[38:39], v[38:39], 1.0 op_sel_hi:[1,0]
	s_nop 0
	v_rcp_f32_e32 v45, v39
	s_nop 0
	v_fma_f32 v46, -v39, v45, 1.0
	v_fmac_f32_e32 v45, v46, v45
	v_mul_f32_e32 v47, v41, v45
	v_fma_f32 v48, -v39, v47, v41
	v_fmac_f32_e32 v47, v48, v45
	v_div_fixup_f32 v39, v47, v39, v41
	v_rcp_f32_e32 v43, v38
	s_nop 0
	v_fma_f32 v45, -v38, v43, 1.0
	v_fmac_f32_e32 v43, v45, v43
	v_mul_f32_e32 v46, v40, v43
	v_fma_f32 v47, -v38, v46, v40
	v_fmac_f32_e32 v46, v47, v43
	v_div_fixup_f32 v38, v46, v38, v40
	v_cvt_pk_bf16_f32 v45, v38, v39
	v_mul_f32_e32 v39, 0xbfb8aa3b, v34
	v_exp_f32_e32 v40, v39
	v_mul_f32_e32 v39, 0xbfb8aa3b, v35
	v_exp_f32_e32 v41, v39
	v_add_u32_e32 v38, 0x2000, v0
	ds_write2_b64 v38, v[54:55], v[44:45] offset0:64 offset1:68
	v_pk_add_f32 v[40:41], v[40:41], 1.0 op_sel_hi:[1,0]
	s_nop 0
	v_rcp_f32_e32 v43, v41
	s_nop 0
	v_fma_f32 v44, -v41, v43, 1.0
	v_fmac_f32_e32 v43, v44, v43
	v_mul_f32_e32 v45, v35, v43
	v_fma_f32 v46, -v41, v45, v35
	v_fmac_f32_e32 v45, v46, v43
	v_div_fixup_f32 v35, v45, v41, v35
	v_rcp_f32_e32 v41, v40
	s_nop 0
	v_fma_f32 v43, -v40, v41, 1.0
	v_fmac_f32_e32 v41, v43, v41
	v_mul_f32_e32 v44, v34, v41
	v_fma_f32 v45, -v40, v44, v34
	v_fmac_f32_e32 v44, v45, v41
	v_div_fixup_f32 v34, v44, v40, v34
	v_cvt_pk_bf16_f32 v40, v34, v35
	v_mul_f32_e32 v34, 0xbfb8aa3b, v36
	v_mul_f32_e32 v35, 0xbfb8aa3b, v37
	v_exp_f32_e32 v34, v34
	v_exp_f32_e32 v35, v35
	s_nop 0
	v_pk_add_f32 v[34:35], v[34:35], 1.0 op_sel_hi:[1,0]
	s_nop 0
	v_rcp_f32_e32 v41, v35
	s_nop 0
	v_fma_f32 v43, -v35, v41, 1.0
	v_fmac_f32_e32 v41, v43, v41
	v_mul_f32_e32 v44, v37, v41
	v_fma_f32 v45, -v35, v44, v37
	v_fmac_f32_e32 v44, v45, v41
	v_div_fixup_f32 v35, v44, v35, v37
	v_rcp_f32_e32 v39, v34
	s_nop 0
	v_fma_f32 v41, -v34, v39, 1.0
	v_fmac_f32_e32 v39, v41, v39
	v_mul_f32_e32 v43, v36, v39
	v_fma_f32 v44, -v34, v43, v36
	v_fmac_f32_e32 v43, v44, v39
	v_div_fixup_f32 v34, v43, v34, v36
	v_cvt_pk_bf16_f32 v41, v34, v35
	v_mul_f32_e32 v35, 0xbfb8aa3b, v30
	v_exp_f32_e32 v36, v35
	v_mul_f32_e32 v35, 0xbfb8aa3b, v31
	v_exp_f32_e32 v37, v35
	v_add_u32_e32 v34, 0x3000, v0
	ds_write2_b64 v34, v[50:51], v[40:41] offset0:96 offset1:100
	v_pk_add_f32 v[36:37], v[36:37], 1.0 op_sel_hi:[1,0]
	s_nop 0
	v_rcp_f32_e32 v39, v37
	s_nop 0
	v_fma_f32 v40, -v37, v39, 1.0
	v_fmac_f32_e32 v39, v40, v39
	v_mul_f32_e32 v41, v31, v39
	v_fma_f32 v43, -v37, v41, v31
	v_fmac_f32_e32 v41, v43, v39
	v_div_fixup_f32 v31, v41, v37, v31
	v_rcp_f32_e32 v37, v36
	s_nop 0
	v_fma_f32 v39, -v36, v37, 1.0
	v_fmac_f32_e32 v37, v39, v37
	v_mul_f32_e32 v40, v30, v37
	v_fma_f32 v41, -v36, v40, v30
	v_fmac_f32_e32 v40, v41, v37
	v_div_fixup_f32 v30, v40, v36, v30
	v_cvt_pk_bf16_f32 v30, v30, v31
	v_mul_f32_e32 v31, 0xbfb8aa3b, v32
	v_exp_f32_e32 v36, v31
	v_mul_f32_e32 v31, 0xbfb8aa3b, v33
	v_exp_f32_e32 v37, v31
	s_nop 0
	v_pk_add_f32 v[36:37], v[36:37], 1.0 op_sel_hi:[1,0]
	s_nop 0
	v_rcp_f32_e32 v35, v37
	s_nop 0
	v_fma_f32 v39, -v37, v35, 1.0
	v_fmac_f32_e32 v35, v39, v35
	v_mul_f32_e32 v40, v33, v35
	v_fma_f32 v41, -v37, v40, v33
	v_fmac_f32_e32 v40, v41, v35
	v_div_fixup_f32 v31, v40, v37, v33
	v_rcp_f32_e32 v35, v36
	s_nop 0
	v_fma_f32 v37, -v36, v35, 1.0
	v_fmac_f32_e32 v35, v37, v35
	v_mul_f32_e32 v39, v32, v35
	v_fma_f32 v40, -v36, v39, v32
	v_fmac_f32_e32 v39, v40, v35
	v_div_fixup_f32 v32, v39, v36, v32
	v_cvt_pk_bf16_f32 v31, v32, v31
	v_mul_f32_e32 v32, 0xbfb8aa3b, v26
	v_mul_f32_e32 v33, 0xbfb8aa3b, v27
	v_exp_f32_e32 v32, v32
	v_exp_f32_e32 v33, v33
	s_nop 0
	v_pk_add_f32 v[32:33], v[32:33], 1.0 op_sel_hi:[1,0]
	s_nop 0
	v_rcp_f32_e32 v36, v33
	s_nop 0
	v_fma_f32 v37, -v33, v36, 1.0
	v_fmac_f32_e32 v36, v37, v36
	v_mul_f32_e32 v39, v27, v36
	v_fma_f32 v40, -v33, v39, v27
	v_fmac_f32_e32 v39, v40, v36
	v_div_fixup_f32 v27, v39, v33, v27
	v_rcp_f32_e32 v35, v32
	s_nop 0
	v_fma_f32 v36, -v32, v35, 1.0
	v_fmac_f32_e32 v35, v36, v35
	v_mul_f32_e32 v37, v26, v35
	v_fma_f32 v39, -v32, v37, v26
	v_fmac_f32_e32 v37, v39, v35
	v_div_fixup_f32 v26, v37, v32, v26
	v_cvt_pk_bf16_f32 v26, v26, v27
	v_mul_f32_e32 v27, 0xbfb8aa3b, v28
	v_exp_f32_e32 v32, v27
	v_mul_f32_e32 v27, 0xbfb8aa3b, v29
	v_exp_f32_e32 v33, v27
	s_nop 0
	v_pk_add_f32 v[32:33], v[32:33], 1.0 op_sel_hi:[1,0]
	s_nop 0
	v_rcp_f32_e32 v35, v33
	s_nop 0
	v_fma_f32 v36, -v33, v35, 1.0
	v_fmac_f32_e32 v35, v36, v35
	v_mul_f32_e32 v37, v29, v35
	v_fma_f32 v39, -v33, v37, v29
	v_fmac_f32_e32 v37, v39, v35
	v_div_fixup_f32 v27, v37, v33, v29
	v_rcp_f32_e32 v33, v32
	s_nop 0
	v_fma_f32 v35, -v32, v33, 1.0
	v_fmac_f32_e32 v33, v35, v33
	v_mul_f32_e32 v36, v28, v33
	v_fma_f32 v37, -v32, v36, v28
	v_fmac_f32_e32 v36, v37, v33
	v_div_fixup_f32 v28, v36, v32, v28
	v_cvt_pk_bf16_f32 v27, v28, v27
	v_mul_f32_e32 v28, 0xbfb8aa3b, v22
	v_mul_f32_e32 v29, 0xbfb8aa3b, v23
	v_exp_f32_e32 v28, v28
	v_exp_f32_e32 v29, v29
	s_nop 0
	v_pk_add_f32 v[28:29], v[28:29], 1.0 op_sel_hi:[1,0]
	s_nop 0
	v_rcp_f32_e32 v33, v29
	s_nop 0
	v_fma_f32 v35, -v29, v33, 1.0
	v_fmac_f32_e32 v33, v35, v33
	v_mul_f32_e32 v36, v23, v33
	v_fma_f32 v37, -v29, v36, v23
	v_fmac_f32_e32 v36, v37, v33
	v_div_fixup_f32 v23, v36, v29, v23
	v_rcp_f32_e32 v32, v28
	s_nop 0
	v_fma_f32 v33, -v28, v32, 1.0
	v_fmac_f32_e32 v32, v33, v32
	v_mul_f32_e32 v35, v22, v32
	v_fma_f32 v36, -v28, v35, v22
	v_fmac_f32_e32 v35, v36, v32
	v_div_fixup_f32 v22, v35, v28, v22
	v_cvt_pk_bf16_f32 v22, v22, v23
	v_mul_f32_e32 v23, 0xbfb8aa3b, v24
	v_exp_f32_e32 v28, v23
	v_mul_f32_e32 v23, 0xbfb8aa3b, v25
	v_exp_f32_e32 v29, v23
	s_nop 0
	v_pk_add_f32 v[28:29], v[28:29], 1.0 op_sel_hi:[1,0]
	s_nop 0
	v_rcp_f32_e32 v32, v29
	s_nop 0
	v_fma_f32 v33, -v29, v32, 1.0
	v_fmac_f32_e32 v32, v33, v32
	v_mul_f32_e32 v35, v25, v32
	v_fma_f32 v36, -v29, v35, v25
	v_fmac_f32_e32 v35, v36, v32
	v_div_fixup_f32 v23, v35, v29, v25
	v_rcp_f32_e32 v29, v28
	s_nop 0
	v_fma_f32 v32, -v28, v29, 1.0
	v_fmac_f32_e32 v29, v32, v29
	v_mul_f32_e32 v33, v24, v29
	v_fma_f32 v35, -v28, v33, v24
	v_fmac_f32_e32 v33, v35, v29
	v_div_fixup_f32 v24, v33, v28, v24
	v_cvt_pk_bf16_f32 v23, v24, v23
	v_mul_f32_e32 v24, 0xbfb8aa3b, v18
	v_mul_f32_e32 v25, 0xbfb8aa3b, v19
	v_exp_f32_e32 v24, v24
	v_exp_f32_e32 v25, v25
	s_nop 0
	v_pk_add_f32 v[24:25], v[24:25], 1.0 op_sel_hi:[1,0]
	s_nop 0
	v_rcp_f32_e32 v29, v25
	s_nop 0
	v_fma_f32 v32, -v25, v29, 1.0
	v_fmac_f32_e32 v29, v32, v29
	v_mul_f32_e32 v33, v19, v29
	v_fma_f32 v35, -v25, v33, v19
	v_fmac_f32_e32 v33, v35, v29
	v_div_fixup_f32 v19, v33, v25, v19
	v_rcp_f32_e32 v28, v24
	s_nop 0
	v_fma_f32 v29, -v24, v28, 1.0
	v_fmac_f32_e32 v28, v29, v28
	v_mul_f32_e32 v32, v18, v28
	v_fma_f32 v33, -v24, v32, v18
	v_fmac_f32_e32 v32, v33, v28
	v_div_fixup_f32 v18, v32, v24, v18
	v_cvt_pk_bf16_f32 v18, v18, v19
	v_mul_f32_e32 v19, 0xbfb8aa3b, v20
	v_exp_f32_e32 v24, v19
	v_mul_f32_e32 v19, 0xbfb8aa3b, v21
	v_exp_f32_e32 v25, v19
	s_nop 0
	v_pk_add_f32 v[24:25], v[24:25], 1.0 op_sel_hi:[1,0]
	s_nop 0
	v_rcp_f32_e32 v28, v25
	s_nop 0
	v_fma_f32 v29, -v25, v28, 1.0
	v_fmac_f32_e32 v28, v29, v28
	v_mul_f32_e32 v32, v21, v28
	v_fma_f32 v33, -v25, v32, v21
	v_fmac_f32_e32 v32, v33, v28
	v_div_fixup_f32 v19, v32, v25, v21
	v_rcp_f32_e32 v25, v24
	s_nop 0
	v_fma_f32 v28, -v24, v25, 1.0
	v_fmac_f32_e32 v25, v28, v25
	v_mul_f32_e32 v29, v20, v25
	v_fma_f32 v32, -v24, v29, v20
	v_fmac_f32_e32 v29, v32, v25
	v_div_fixup_f32 v20, v29, v24, v20
	v_cvt_pk_bf16_f32 v19, v20, v19
	v_mul_f32_e32 v20, 0xbfb8aa3b, v14
	v_mul_f32_e32 v21, 0xbfb8aa3b, v15
	v_exp_f32_e32 v20, v20
	v_exp_f32_e32 v21, v21
	s_nop 0
	v_pk_add_f32 v[20:21], v[20:21], 1.0 op_sel_hi:[1,0]
	s_nop 0
	v_rcp_f32_e32 v25, v21
	s_nop 0
	v_fma_f32 v28, -v21, v25, 1.0
	v_fmac_f32_e32 v25, v28, v25
	v_mul_f32_e32 v29, v15, v25
	v_fma_f32 v32, -v21, v29, v15
	v_fmac_f32_e32 v29, v32, v25
	v_div_fixup_f32 v15, v29, v21, v15
	v_rcp_f32_e32 v24, v20
	s_nop 0
	v_fma_f32 v25, -v20, v24, 1.0
	v_fmac_f32_e32 v24, v25, v24
	v_mul_f32_e32 v28, v14, v24
	v_fma_f32 v29, -v20, v28, v14
	v_fmac_f32_e32 v28, v29, v24
	v_div_fixup_f32 v14, v28, v20, v14
	v_cvt_pk_bf16_f32 v14, v14, v15
	v_mul_f32_e32 v15, 0xbfb8aa3b, v16
	v_exp_f32_e32 v20, v15
	v_mul_f32_e32 v15, 0xbfb8aa3b, v17
	v_exp_f32_e32 v21, v15
	s_nop 0
	v_pk_add_f32 v[20:21], v[20:21], 1.0 op_sel_hi:[1,0]
	s_nop 0
	v_rcp_f32_e32 v24, v21
	s_nop 0
	v_fma_f32 v25, -v21, v24, 1.0
	v_fmac_f32_e32 v24, v25, v24
	v_mul_f32_e32 v28, v17, v24
	v_fma_f32 v29, -v21, v28, v17
	v_fmac_f32_e32 v28, v29, v24
	v_div_fixup_f32 v15, v28, v21, v17
	v_rcp_f32_e32 v21, v20
	s_nop 0
	v_fma_f32 v24, -v20, v21, 1.0
	v_fmac_f32_e32 v21, v24, v21
	v_mul_f32_e32 v25, v16, v21
	v_fma_f32 v28, -v20, v25, v16
	v_fmac_f32_e32 v25, v28, v21
	v_div_fixup_f32 v16, v25, v20, v16
	v_cvt_pk_bf16_f32 v15, v16, v15
	ds_write2_b64 v0, v[30:31], v[14:15] offset0:8 offset1:12
	v_mul_f32_e32 v0, 0xbfb8aa3b, v10
	v_exp_f32_e32 v14, v0
	v_mul_f32_e32 v0, 0xbfb8aa3b, v11
	v_exp_f32_e32 v15, v0
	s_nop 0
	v_pk_add_f32 v[14:15], v[14:15], 1.0 op_sel_hi:[1,0]
	s_nop 0
	v_rcp_f32_e32 v16, v15
	s_nop 0
	v_fma_f32 v17, -v15, v16, 1.0
	v_fmac_f32_e32 v16, v17, v16
	v_mul_f32_e32 v20, v11, v16
	v_fma_f32 v21, -v15, v20, v11
	v_fmac_f32_e32 v20, v21, v16
	v_div_fixup_f32 v0, v20, v15, v11
	v_rcp_f32_e32 v15, v14
	s_nop 0
	v_fma_f32 v16, -v14, v15, 1.0
	v_fmac_f32_e32 v15, v16, v15
	v_mul_f32_e32 v17, v10, v15
	v_fma_f32 v20, -v14, v17, v10
	v_fmac_f32_e32 v17, v20, v15
	v_div_fixup_f32 v10, v17, v14, v10
	v_cvt_pk_bf16_f32 v10, v10, v0
	v_mul_f32_e32 v0, 0xbfb8aa3b, v12
	v_exp_f32_e32 v14, v0
	v_mul_f32_e32 v0, 0xbfb8aa3b, v13
	v_exp_f32_e32 v15, v0
	s_nop 0
	v_pk_add_f32 v[14:15], v[14:15], 1.0 op_sel_hi:[1,0]
	s_nop 0
	v_rcp_f32_e32 v11, v15
	s_nop 0
	v_fma_f32 v16, -v15, v11, 1.0
	v_fmac_f32_e32 v11, v16, v11
	v_mul_f32_e32 v17, v13, v11
	v_fma_f32 v20, -v15, v17, v13
	v_fmac_f32_e32 v17, v20, v11
	v_div_fixup_f32 v0, v17, v15, v13
	v_rcp_f32_e32 v13, v14
	s_nop 0
	v_fma_f32 v15, -v14, v13, 1.0
	v_fmac_f32_e32 v13, v15, v13
	v_mul_f32_e32 v16, v12, v13
	v_fma_f32 v17, -v14, v16, v12
	v_fmac_f32_e32 v16, v17, v13
	v_div_fixup_f32 v11, v16, v14, v12
	v_cvt_pk_bf16_f32 v11, v11, v0
	v_mul_f32_e32 v0, 0xbfb8aa3b, v6
	ds_write2_b64 v42, v[26:27], v[10:11] offset0:40 offset1:44
	v_exp_f32_e32 v10, v0
	v_mul_f32_e32 v0, 0xbfb8aa3b, v7
	v_exp_f32_e32 v11, v0
	s_nop 0
	v_pk_add_f32 v[10:11], v[10:11], 1.0 op_sel_hi:[1,0]
	s_nop 0
	v_rcp_f32_e32 v12, v11
	s_nop 0
	v_fma_f32 v13, -v11, v12, 1.0
	v_fmac_f32_e32 v12, v13, v12
	v_mul_f32_e32 v14, v7, v12
	v_fma_f32 v15, -v11, v14, v7
	v_fmac_f32_e32 v14, v15, v12
	v_div_fixup_f32 v0, v14, v11, v7
	v_rcp_f32_e32 v11, v10
	s_nop 0
	v_fma_f32 v12, -v10, v11, 1.0
	v_fmac_f32_e32 v11, v12, v11
	v_mul_f32_e32 v13, v6, v11
	v_fma_f32 v14, -v10, v13, v6
	v_fmac_f32_e32 v13, v14, v11
	v_div_fixup_f32 v6, v13, v10, v6
	v_cvt_pk_bf16_f32 v6, v6, v0
	v_mul_f32_e32 v0, 0xbfb8aa3b, v8
	v_exp_f32_e32 v10, v0
	v_mul_f32_e32 v0, 0xbfb8aa3b, v9
	v_exp_f32_e32 v11, v0
	s_nop 0
	v_pk_add_f32 v[10:11], v[10:11], 1.0 op_sel_hi:[1,0]
	s_nop 0
	v_rcp_f32_e32 v7, v11
	s_nop 0
	v_fma_f32 v12, -v11, v7, 1.0
	v_fmac_f32_e32 v7, v12, v7
	v_mul_f32_e32 v13, v9, v7
	v_fma_f32 v14, -v11, v13, v9
	v_fmac_f32_e32 v13, v14, v7
	v_div_fixup_f32 v0, v13, v11, v9
	v_rcp_f32_e32 v9, v10
	s_nop 0
	v_fma_f32 v11, -v10, v9, 1.0
	v_fmac_f32_e32 v9, v11, v9
	v_mul_f32_e32 v12, v8, v9
	v_fma_f32 v13, -v10, v12, v8
	v_fmac_f32_e32 v12, v13, v9
	v_div_fixup_f32 v7, v12, v10, v8
	v_cvt_pk_bf16_f32 v7, v7, v0
	v_mul_f32_e32 v0, 0xbfb8aa3b, v2
	ds_write2_b64 v38, v[22:23], v[6:7] offset0:72 offset1:76
	v_exp_f32_e32 v6, v0
	v_mul_f32_e32 v0, 0xbfb8aa3b, v3
	v_exp_f32_e32 v7, v0
	s_nop 0
	v_pk_add_f32 v[6:7], v[6:7], 1.0 op_sel_hi:[1,0]
	s_nop 0
	v_rcp_f32_e32 v8, v7
	s_nop 0
	v_fma_f32 v9, -v7, v8, 1.0
	v_fmac_f32_e32 v8, v9, v8
	v_mul_f32_e32 v10, v3, v8
	v_fma_f32 v11, -v7, v10, v3
	v_fmac_f32_e32 v10, v11, v8
	v_div_fixup_f32 v0, v10, v7, v3
	v_rcp_f32_e32 v7, v6
	s_nop 0
	v_fma_f32 v8, -v6, v7, 1.0
	v_fmac_f32_e32 v7, v8, v7
	v_mul_f32_e32 v9, v2, v7
	v_fma_f32 v10, -v6, v9, v2
	v_fmac_f32_e32 v9, v10, v7
	v_div_fixup_f32 v2, v9, v6, v2
	v_cvt_pk_bf16_f32 v2, v2, v0
	v_mul_f32_e32 v0, 0xbfb8aa3b, v4
	v_exp_f32_e32 v6, v0
	v_mul_f32_e32 v0, 0xbfb8aa3b, v5
	v_exp_f32_e32 v7, v0
	s_nop 0
	v_pk_add_f32 v[6:7], v[6:7], 1.0 op_sel_hi:[1,0]
	s_nop 0
	v_rcp_f32_e32 v3, v7
	s_nop 0
	v_fma_f32 v8, -v7, v3, 1.0
	v_fmac_f32_e32 v3, v8, v3
	v_mul_f32_e32 v9, v5, v3
	v_fma_f32 v10, -v7, v9, v5
	v_fmac_f32_e32 v9, v10, v3
	v_div_fixup_f32 v0, v9, v7, v5
	v_rcp_f32_e32 v5, v6
	s_nop 0
	v_fma_f32 v7, -v6, v5, 1.0
	v_fmac_f32_e32 v5, v7, v5
	v_mul_f32_e32 v8, v4, v5
	v_fma_f32 v9, -v6, v8, v4
	v_fmac_f32_e32 v8, v9, v5
	v_div_fixup_f32 v3, v8, v6, v4
	v_cvt_pk_bf16_f32 v3, v3, v0
	ds_write2_b64 v34, v[18:19], v[2:3] offset0:104 offset1:108
	s_waitcnt lgkmcnt(0)
	s_barrier
	s_mov_b64 s[38:39], -1
	s_and_b64 vcc, exec, s[28:29]
	s_cbranch_vccz .LBB0_269
